# v054 + last-layer GEMM tile-space compaction (context M-panels removed from the tile index: 2048/2048/512 tiles, no third G5 round)
# speedup vs baseline: 1.0146x; 1.0040x over previous
; __device__ void gemm_step(const P& p, int step, int l) {
;     ...
;   int ntiles;
;   const int nbr = 1;
;   if (step == 1) ntiles = nM * (NP / BNT);
;   else if (step == 3) ntiles = nM * (2304 / BNT);
;   else if (step == 6) ntiles = 4 * nM * (2048 / BNT);
;   else if (step == 7) ntiles = nM * 32;
;   else ntiles = nM * (2048 / BNT);
;   for (int t0 = BIDX; t0 < (ntiles + 255) / 256 * 256; t0 += gridDim.x) {
.LBB0_160:
	s_cmp_gt_u32 s77, 53
	s_cbranch_scc0 .Lcmp_nt
	s_and_b64 vcc, exec, s[28:29]
	s_cbranch_vccz .Lcmp_nt
	s_movk_i32 s4, 0x800
	s_cmpk_eq_i32 s86, 0x220
	s_cselect_b32 s86, 0x200, s4

; __device__ void gemm_step(const P& p, int step, int l) {
;     ...
;     const int t = xcd_remap(t0, BIDX, gridDim.x);
;     if (t >= ntiles) continue;
;     for (int br = 0; br < nbr; ++br) {
;       const u16 *A, *Bt;
;       int lda, ldb, K, pm, pn, mode, aux = 0, bmode = 0, ncol = BNT;
;       if (step == 1) {
;         tile_map(t, nM, NP / BNT, pm, pn);
;         A = (const u16*)(ws + O_HN); lda = 2048; Bt = (const u16*)(ws + O_WIN); ldb = 2048; K = 2048; mode = M_G1A;
;       } else if (step == 3) {
;         const int c2 = 768 / BNT, c3 = 1024 / BNT, c4 = 512 / BNT; const int n2 = nM * c2, n3 = nM * c3;
;         K = 512; ldb = 512;
;         if (t < n2) {
;           pm = t / c2; pn = t % c2; A = (const u16*)(ws + O_PROJ) + C_CQ; lda = NP; Bt = (const u16*)(ws + O_WUQ); mode = M_G2;
;         } else if (t < n2 + n3) {
;           int tt = t - n2; pm = tt / c3; pn = tt % c3; A = (const u16*)(ws + O_PROJ) + C_CKV; lda = NP; Bt = (const u16*)(ws + O_WUKV); mode = M_G3;
;         } else {
;           int tt = t - n2 - n3; pm = tt / c4; pn = tt % c4; A = (const u16*)(ws + O_DPOOL); lda = 512; Bt = (const u16*)(ws + O_POOL); mode = M_POOL;
;         }
;       } else if (step == 6) {
;         aux = t / (nM * (2048 / BNT));
;         tile_map(t % (nM * (2048 / BNT)), nM, 2048 / BNT, pm, pn);
;         A = (const u16*)(ws + O_YS) + aux * 512; lda = 2048; Bt = (const u16*)(ws + O_WBR) + (size_t)aux * 2048 * 512; ldb = 512; K = 512; mode = M_G4;
.Lhm_nomap:
.LBB0_166:
	s_cmp_ge_i32 s8, s86
	s_cbranch_scc1 .LBB0_163
	s_and_b64 vcc, exec, s[40:41]
	s_cbranch_vccnz .LBB0_172
	v_readlane_b32 s4, v249, 56
	s_mov_b64 s[2:3], -1
	s_mov_b64 s[56:57], 0
	s_cmp_lt_i32 s4, 6
	s_mov_b64 s[54:55], 0
	s_cbranch_scc1 .LBB0_173
	s_mul_hi_i32 s2, s8, 0x78787879
	s_lshr_b32 s3, s2, 31
	s_ashr_i32 s2, s2, 8
	s_add_i32 s36, s2, s3
	s_and_b64 vcc, exec, s[24:25]
	s_cbranch_vccz .Lcmp_aux
	s_lshr_b32 s36, s8, 9
.Lcmp_aux:
	s_ashr_i32 s37, s36, 31
	s_lshl_b64 s[2:3], s[36:37], 21
	v_readlane_b32 s4, v248, 3
	s_add_u32 s28, s4, s2
	v_readlane_b32 s2, v248, 5
	s_addc_u32 s29, s2, s3
	s_lshl_b32 s2, s36, 9
	s_ashr_i32 s3, s2, 31
	s_lshl_b64 s[2:3], s[2:3], 1
	v_readlane_b32 s4, v248, 2
	s_add_u32 s44, s4, s2
	v_readlane_b32 s2, v249, 56
	s_addc_u32 s45, s75, s3
	s_and_b32 s4, 0xffff, s2
	s_cmp_gt_i32 s4, 6
	s_mov_b64 s[2:3], 0
	s_cbranch_scc0 .LBB0_178
	s_cmp_eq_u32 s4, 7
	s_mov_b64 s[34:35], 0
	s_cbranch_scc0 .LBB0_316
	s_ashr_i32 s4, s8, 31
	s_lshr_b32 s4, s4, 25
	s_add_i32 s4, s8, s4
	s_ashr_i32 s5, s4, 7
	s_and_b32 s4, s4, 0xffffff80
	s_sub_i32 s6, s8, s4
	s_lshl_b32 s4, s5, 2
	s_and_b32 s5, s6, 3
	s_or_b32 s4, s5, s4
	s_ashr_i32 s6, s6, 2
	s_mov_b64 s[46:47], 0
	s_movk_i32 s5, 0x800
	s_mov_b64 s[36:37], -1
	s_mov_b32 s71, 5
	s_mov_b32 s7, 64
	s_branch .LBB0_317

; __device__ void gemm_step(const P& p, int step, int l) {
;     ...
;         aux = t / (nM * (2048 / BNT));
;         tile_map(t % (nM * (2048 / BNT)), nM, 2048 / BNT, pm, pn);
.LBB0_178:
	s_movk_i32 s4, 0x220
	s_and_b64 vcc, exec, s[24:25]
	s_cbranch_vccz .Lcmp_rem
	s_movk_i32 s4, 0x200
.Lcmp_rem:
	s_mul_i32 s4, s36, s4
	s_sub_i32 s4, s8, s4
	s_bfe_u32 s5, s4, 0x5001a
	s_add_i32 s5, s4, s5
	s_sext_i32_i16 s7, s5
	s_and_b32 s5, s5, 0xffe0
	s_sub_i32 s4, s4, s5
	s_sext_i32_i16 s4, s4
	s_ashr_i32 s5, s7, 5
	s_lshl_b32 s34, s36, 11
	s_ashr_i32 s6, s4, 2
	s_and_b32 s4, s4, 3
	s_lshl_b32 s5, s5, 2
	s_ashr_i32 s35, s34, 31
	s_or_b32 s4, s4, s5
	s_movk_i32 s5, 0x200
	s_mov_b64 s[46:47], -1
	s_mov_b32 s71, 4
	s_movk_i32 s7, 0x100
	s_mov_b64 s[36:37], 0
	s_and_b64 vcc, exec, s[2:3]
	s_cbranch_vccnz .LBB0_174

; __device__ void gemm_step(const P& p, int step, int l) {
;     ...
;       if (step >= 6 && !need_ctx && (pm % 17) == 0) continue;
;       gemm256(p, A, lda, Bt, ldb, K, pm * 256, pn * ncol, mode, aux, l, bmode);
.LBB0_184:
	s_and_b64 vcc, exec, s[24:25]
	s_cbranch_vccz .Lcmp_pm
	s_lshr_b32 s2, s4, 4
	s_add_i32 s4, s4, s2
	s_add_i32 s4, s4, 1
